# up GEMM: per-XCD atomic ticket tile order from each workgroup 4th tile on (LDS broadcast, 2-unit lookahead)
# baseline (speedup 1.0000x reference)
; __global__ void __launch_bounds__(NWAVES * 64, 2) mk_fwd(Args args) {
;     ...
;         bf16* HB = (bf16*)(ws + WS_HB); bf16* VAb = (bf16*)(ws + WS_VA); bf16* Ub = (bf16*)(ws + WS_U); bf16* Vb = (bf16*)(ws + WS_V); bf16* Qb = (bf16*)(ws + WS_Q); bf16* Kb = (bf16*)(ws + WS_K);
;         bf16* TMP = (bf16*)(ws + WS_TMP); bf16* ACT = (bf16*)(ws + WS_ACT);
;         float* lamw = (float*)(ws + WS_LAM); float* tabw = (float*)(ws + WS_TAB); float* vss = (float*)(ws + WS_VSS);
;     ...
;             const int l = (ph - 1) / 7, k = (ph - 1) % 7;
;             unsigned char* wl = ws + WS_W + (size_t)l * WL_STRIDE; float* rss = (float*)(ws + WS_RSS);
.LBB0_31:
	s_add_i32 s2, s74, -1
	s_mul_hi_i32 s3, s2, 0x92492493
	s_add_i32 s3, s3, s2
	s_lshr_b32 s4, s3, 31
	s_ashr_i32 s3, s3, 2
	s_add_i32 s62, s3, s4
	s_lshl_b32 s99, s62, 6
	s_add_i32 s99, s99, 0xb800
	s_mul_i32 s3, s62, 7
	s_sub_i32 s4, s2, s3
	s_ashr_i32 s63, s62, 31
	s_mul_i32 s3, s62, 0x2480000
	s_mul_hi_i32 s2, s62, 0x2480000
	s_add_u32 s3, s22, s3
	s_addc_u32 s2, s23, s2
	s_add_u32 s3, s3, 0x400000
	v_writelane_b32 v254, s3, 35
	s_addc_u32 s2, s2, 0
	v_writelane_b32 v254, s2, 36
	s_add_u32 s2, s22, 0x4e00000
	s_addc_u32 s3, s23, 0
	s_add_u32 s36, s22, 0x7000000
	s_addc_u32 s37, s23, 0
	s_add_u32 s28, s22, 0xb000000
	s_addc_u32 s29, s23, 0
	s_add_u32 s12, s22, 0xf000000
	s_addc_u32 s13, s23, 0
	s_add_u32 s42, s22, 0x13000000
	s_addc_u32 s43, s23, 0
	v_writelane_b32 v254, s2, 37
	s_add_u32 s34, s22, 0x17000000
	s_mov_b64 s[10:11], 0
	v_writelane_b32 v254, s3, 38
	s_addc_u32 s2, s23, 0
	s_add_u32 s26, s22, 0x1b000000
	v_writelane_b32 v254, s2, 39
	s_addc_u32 s27, s23, 0
	v_writelane_b32 v254, s4, 40
	s_cmp_lt_i32 s4, 3
	s_mov_b64 s[4:5], 0
	v_writelane_b32 v254, s4, 41
	s_mov_b64 s[2:3], -1
	s_nop 0
	v_writelane_b32 v254, s5, 42
	v_writelane_b32 v254, s0, 43
	s_nop 1
	v_writelane_b32 v254, s1, 44
	s_cbranch_scc1 .LBB0_170
	v_readlane_b32 s2, v254, 40
	s_cmp_gt_i32 s2, 3
	s_cbranch_scc0 .LBB0_35
	s_cmp_gt_i32 s2, 5
	s_cbranch_scc0 .LBB0_36
	s_mov_b64 s[6:7], -1
	v_writelane_b32 v254, s6, 41
	s_cmp_eq_u32 s2, 6
	s_nop 0
	v_writelane_b32 v254, s7, 42
	s_cselect_b64 s[2:3], -1, 0
	s_cbranch_execz .LBB0_37
	s_branch .LBB0_38

;     __host__ __device__ bool next(int i, Unit& u) const {
;         const long L = (long)i * G + c; if (L >= nwg) return false;
;         int wgid = (int)L; { const int q = nwg / NXCD, r = nwg % NXCD, xcd = wgid % NXCD, off = wgid / NXCD; wgid = (xcd < r ? xcd * (q + 1) : r * (q + 1) + (xcd - r) * q) + off; }
;         const int nig = WGM * nN, gid = wgid / nig, fm = gid * WGM, gsz = (nM - fm) < WGM ? (nM - fm) : WGM;
;         u.pm = fm + ((wgid % nig) % gsz); u.pn = (wgid % nig) / gsz; return true;
.LBB0_283:
	s_add_i32 s97, s97, 1
	s_cmp_lt_u32 s97, 3
	s_cbranch_scc1 .Lup_static
	s_and_b32 s98, s90, 7
	s_cmp_lg_u32 s98, 0
	s_cbranch_scc1 .Lup_static
	s_and_b32 s98, s97, 1
	s_lshl_b32 s98, s98, 2
	s_add_u32 s98, s98, 0x23e00
	v_mov_b32_e32 v0, s98
	ds_read_b32 v0, v0
	s_waitcnt lgkmcnt(0)
	v_readfirstlane_b32 s6, v0
	s_lshr_b32 s98, s90, 3
	s_mul_i32 s98, s98, 3
	s_add_i32 s6, s6, s98
	s_lshl_b32 s6, s6, 3
	s_and_b32 s98, s89, 7
	s_or_b32 s6, s6, s98
	s_mov_b32 s7, 0
	s_branch .Lup_have_L
.Lup_static:
	s_mul_i32 s4, s97, s31
	s_mul_hi_u32 s5, s97, s90
	s_add_i32 s5, s5, s4
	s_mul_i32 s4, s97, s90
	s_add_u32 s6, s4, s89
	s_addc_u32 s7, s5, s35
.Lup_have_L:
	v_mov_b64_e32 v[0:1], 0xbb0
	v_cmp_lt_i64_e64 s[4:5], s[6:7], v[0:1]
	v_mov_b64_e32 v[0:1], 0xbaf
	v_cmp_gt_i64_e32 vcc, s[6:7], v[0:1]
	s_cbranch_vccnz .LBB0_285
	s_ashr_i32 s7, s6, 31
	s_lshr_b32 s7, s7, 29
	s_add_i32 s7, s6, s7
	s_ashr_i32 s9, s7, 3
	s_and_b32 s7, s7, -8
	s_sub_i32 s6, s6, s7
	s_cmp_lt_i32 s6, 0
	s_movk_i32 s7, 0x177
	s_cselect_b32 s7, s7, 0x176
	s_mul_i32 s6, s6, s7
	s_add_i32 s6, s6, s9
	s_mul_hi_i32 s7, s6, 0x2e8ba2e9
	s_lshr_b32 s9, s7, 31
	s_ashr_i32 s7, s7, 5
	s_add_i32 s7, s7, s9
	s_lshl_b32 s9, s7, 3
	s_sub_i32 s18, 0x88, s9
	s_min_i32 s18, s18, 8
	s_abs_i32 s19, s18
	v_cvt_f32_u32_e32 v0, s19
	s_sub_i32 s56, 0, s19
	s_mulk_i32 s7, 0xb0
	s_sub_i32 s6, s6, s7
	v_rcp_iflag_f32_e32 v0, v0
	s_abs_i32 s7, s6
	s_xor_b32 s38, s6, s18
	s_ashr_i32 s38, s38, 31
	v_mul_f32_e32 v0, 0x4f7ffffe, v0
	v_cvt_u32_f32_e32 v0, v0
	s_nop 0
	v_readfirstlane_b32 s57, v0
	s_mul_i32 s56, s56, s57
	s_mul_hi_u32 s56, s57, s56
	s_add_i32 s57, s57, s56
	s_mul_hi_u32 s56, s7, s57
	s_mul_i32 s57, s56, s19
	s_sub_i32 s7, s7, s57
	s_add_i32 s70, s56, 1
	s_sub_i32 s57, s7, s19
	s_cmp_ge_u32 s7, s19
	s_cselect_b32 s56, s70, s56
	s_cselect_b32 s7, s57, s7
	s_add_i32 s57, s56, 1
	s_cmp_ge_u32 s7, s19
	s_cselect_b32 s7, s57, s56
	s_xor_b32 s7, s7, s38
	s_sub_i32 s70, s7, s38
	s_mul_i32 s7, s70, s18
	s_sub_i32 s6, s6, s7
	s_add_i32 s38, s9, s6

; #define PG8_LAS __attribute__((address_space(3)))
;     __device__ __forceinline__ void operator()(const f32x4 (&acc)[2][2][4][2], const Unit& u, int wr, int wc, int fr, int fq) const {
;         const int b = u.pm / 17, i = u.pm - b * 17, fl = wc * 32 + 8 * fq, f0 = u.pn * 128 + fl;
;         float rn[2][4];
; #pragma unroll
;         for (int ai = 0; ai < 2; ++ai)
; #pragma unroll
;             for (int m = 0; m < 4; ++m) rn[ai][m] = row_rstd(rss, (long)b * 4096 + 254 * i - 2 + ai * HALF + wr * 64 + m * 16 + fr, fq);
;         if (fr >= 14) {
; #pragma unroll
;             for (int ai = 0; ai < 2; ++ai)
; #pragma unroll
;                 for (int n = 0; n < 2; ++n) *(PG8_LAS f32x4*)(halo + ((ai * 2 + wr) * 2 + (fr - 14)) * 128 + fl + 4 * n) = acc[ai][0][3][n] * rn[ai][3];
.LBB0_291:
	v_readlane_b32 s98, v254, 25
	s_nop 1
	s_cmp_lg_u32 s98, 0
	s_cbranch_scc1 .Lup_tk_skip
	v_readlane_b32 s100, v254, 4
	v_readlane_b32 s101, v254, 5
	s_nop 4
	s_load_dwordx2 s[100:101], s[100:101], 0xb8
	s_and_b32 s98, s89, 7
	s_lshl_b32 s98, s98, 2
	s_add_u32 s98, s98, s99
	s_waitcnt lgkmcnt(0)
	s_add_u32 s100, s100, s98
	s_addc_u32 s101, s101, 0
	s_mov_b64 exec, 1
	v_mov_b32_e32 v98, 1
	global_atomic_add v98, v209, v98, s[100:101] sc0
	s_mov_b64 exec, -1
.Lup_tk_skip:
	s_mul_hi_i32 s4, s86, 0x78787879
	s_lshr_b32 s5, s4, 31
	s_ashr_i32 s4, s4, 3
	s_add_i32 s76, s4, s5
	s_mul_i32 s4, s76, 0xffffffef
	s_add_i32 s6, s4, s86
	s_ashr_i32 s77, s76, 31
	s_lshl_b64 s[4:5], s[76:77], 12
	s_mul_i32 s77, s6, 0xfe
	s_ashr_i32 s6, s77, 31
	s_add_u32 s4, s77, s4
	s_addc_u32 s5, s6, s5
	v_cmp_lt_i32_e32 vcc, v251, v246
	v_lshl_add_u64 v[64:65], s[4:5], 0, v[174:175]
	v_lshlrev_b64 v[64:65], 6, v[64:65]
	v_cndmask_b32_e32 v66, v245, v251, vcc
	v_cmp_lt_i32_e32 vcc, v252, v246
	v_lshlrev_b32_e32 v69, 2, v66
	s_mov_b32 s78, 0x3a800000
	v_cndmask_b32_e32 v66, v245, v252, vcc
	v_lshlrev_b32_e32 v68, 2, v66
	v_lshl_add_u64 v[66:67], v[176:177], 0, v[64:65]
	v_add_co_u32_e32 v96, vcc, 0x2000, v66
	s_nop 1
	v_addc_co_u32_e32 v97, vcc, 0, v67, vcc
	global_load_dwordx4 v[220:223], v[66:67], off
	global_load_dwordx4 v[224:227], v[66:67], off offset:1024
	global_load_dwordx4 v[228:231], v[66:67], off offset:2048
	global_load_dwordx4 v[232:235], v[66:67], off offset:3072
	global_load_dwordx4 v[236:239], v[96:97], off
	global_load_dwordx4 v[240:243], v[96:97], off offset:1024
	global_load_dwordx4 v[88:91], v[96:97], off offset:2048
	global_load_dwordx4 v[92:95], v[96:97], off offset:3072
	s_movk_i32 s6, 0x2000
	s_waitcnt vmcnt(7)
	v_mov_b32_e32 v70, v220
	v_mov_b32_e32 v71, v221
	v_mov_b32_e32 v72, v222
	v_mov_b32_e32 v73, v223
	v_readlane_b32 s98, v254, 25
	s_nop 1
	s_cmp_lg_u32 s98, 0
	s_cbranch_scc1 .Lup_tk_skip2
	s_and_b32 s98, s97, 1
	s_lshl_b32 s98, s98, 2
	s_add_u32 s98, s98, 0x23e00
	s_mov_b64 exec, 1
	v_mov_b32_e32 v99, s98
	ds_write_b32 v99, v98
	s_mov_b64 exec, -1
.Lup_tk_skip2:
	v_mov_b32_e32 v64, v71
	v_mov_b32_e32 v65, v72
	v_mov_b32_e32 v71, v73
	v_pk_add_f32 v[64:65], v[64:65], v[70:71]
	s_waitcnt vmcnt(6)
	v_mov_b32_e32 v70, v224
	v_mov_b32_e32 v71, v225
	v_mov_b32_e32 v72, v226
	v_mov_b32_e32 v73, v227
	v_mov_b32_e32 v74, v71
	v_mov_b32_e32 v75, v72
	v_mov_b32_e32 v71, v73
	v_pk_add_f32 v[70:71], v[74:75], v[70:71]
	v_mov_b32_e32 v73, v64
	v_mov_b32_e32 v72, v70
	v_mov_b32_e32 v64, v71
	v_pk_add_f32 v[64:65], v[72:73], v[64:65]
	ds_bpermute_b32 v71, v69, v65
	ds_bpermute_b32 v70, v69, v64
	s_waitcnt lgkmcnt(0)
	v_pk_add_f32 v[192:193], v[64:65], v[70:71]
	ds_bpermute_b32 v195, v68, v193
	ds_bpermute_b32 v194, v68, v192
	s_waitcnt vmcnt(5)
	v_mov_b32_e32 v70, v228
	v_mov_b32_e32 v71, v229
	v_mov_b32_e32 v72, v230
	v_mov_b32_e32 v73, v231
	v_mov_b32_e32 v64, v71
	v_mov_b32_e32 v65, v72
	v_mov_b32_e32 v71, v73
	v_pk_add_f32 v[64:65], v[64:65], v[70:71]
	s_waitcnt vmcnt(4)
	v_mov_b32_e32 v70, v232
	v_mov_b32_e32 v71, v233
	v_mov_b32_e32 v72, v234
	v_mov_b32_e32 v73, v235
	v_mov_b32_e32 v74, v71
	v_mov_b32_e32 v75, v72
	v_mov_b32_e32 v71, v73
	v_pk_add_f32 v[70:71], v[74:75], v[70:71]
	v_mov_b32_e32 v73, v64
	v_mov_b32_e32 v72, v70
	v_mov_b32_e32 v64, v71
	v_pk_add_f32 v[64:65], v[72:73], v[64:65]
	ds_bpermute_b32 v71, v69, v65
	ds_bpermute_b32 v70, v69, v64
	s_waitcnt lgkmcnt(0)
	v_pk_add_f32 v[64:65], v[64:65], v[70:71]
	ds_bpermute_b32 v71, v68, v65
	ds_bpermute_b32 v70, v68, v64
	s_waitcnt lgkmcnt(0)
	v_pk_add_f32 v[70:71], v[64:65], v[70:71]
	v_mov_b64_e32 v[64:65], s[0:1]
	v_pk_fma_f32 v[186:187], v[70:71], s[78:79], v[64:65] op_sel_hi:[1,0,0]
	s_nop 0
	v_cmp_gt_f32_e32 vcc, s39, v186
	v_mul_f32_e32 v70, 0x4b800000, v186
	v_cmp_gt_f32_e64 s[4:5], s39, v187
	v_cndmask_b32_e32 v70, v186, v70, vcc
	v_rsq_f32_e32 v70, v70
	s_nop 0
	v_mul_f32_e32 v71, 0x45800000, v70
	v_cndmask_b32_e32 v186, v70, v71, vcc
	v_add_co_u32_e32 v66, vcc, s6, v66
	s_nop 1
	v_addc_co_u32_e32 v67, vcc, 0, v67, vcc
	s_waitcnt vmcnt(3)
	v_mov_b32_e32 v70, v236
	v_mov_b32_e32 v71, v237
	v_mov_b32_e32 v72, v238
	v_mov_b32_e32 v73, v239
	v_mov_b32_e32 v74, v71
	v_mov_b32_e32 v75, v72
	v_mov_b32_e32 v71, v73
	v_pk_add_f32 v[74:75], v[74:75], v[70:71]
	s_waitcnt vmcnt(2)
	v_mov_b32_e32 v70, v240
	v_mov_b32_e32 v71, v241
	v_mov_b32_e32 v72, v242
	v_mov_b32_e32 v73, v243
	v_mov_b32_e32 v76, v71
	v_mov_b32_e32 v77, v72
	v_mov_b32_e32 v71, v73
	v_pk_add_f32 v[70:71], v[76:77], v[70:71]
	v_mov_b32_e32 v73, v74
	v_mov_b32_e32 v72, v70
	v_mov_b32_e32 v74, v71
	v_pk_add_f32 v[70:71], v[72:73], v[74:75]
	ds_bpermute_b32 v73, v69, v71
	ds_bpermute_b32 v72, v69, v70
	s_waitcnt lgkmcnt(0)
	v_pk_add_f32 v[188:189], v[70:71], v[72:73]
	ds_bpermute_b32 v191, v68, v189
	ds_bpermute_b32 v190, v68, v188
	s_waitcnt vmcnt(1)
	v_mov_b32_e32 v70, v88
	v_mov_b32_e32 v71, v89
	v_mov_b32_e32 v72, v90
	v_mov_b32_e32 v73, v91
	v_mov_b32_e32 v74, v71
	v_mov_b32_e32 v75, v72
	v_mov_b32_e32 v71, v73
	v_pk_add_f32 v[74:75], v[74:75], v[70:71]
	s_waitcnt vmcnt(0)
	v_mov_b32_e32 v70, v92
	v_mov_b32_e32 v71, v93
	v_mov_b32_e32 v72, v94
	v_mov_b32_e32 v73, v95
	v_mov_b32_e32 v66, v71
	v_mov_b32_e32 v67, v72
	v_mov_b32_e32 v71, v73
	v_pk_add_f32 v[66:67], v[66:67], v[70:71]
	v_mov_b32_e32 v71, v74
	v_mov_b32_e32 v70, v66
	v_mov_b32_e32 v74, v67
	v_pk_add_f32 v[66:67], v[70:71], v[74:75]
	ds_bpermute_b32 v71, v69, v67
	ds_bpermute_b32 v70, v69, v66
	s_waitcnt lgkmcnt(0)
	v_pk_add_f32 v[66:67], v[66:67], v[70:71]
	ds_bpermute_b32 v69, v68, v67
	ds_bpermute_b32 v68, v68, v66
	s_waitcnt lgkmcnt(0)
	v_pk_add_f32 v[66:67], v[66:67], v[68:69]
	s_nop 0
	v_pk_fma_f32 v[184:185], v[66:67], s[78:79], v[64:65] op_sel_hi:[1,0,0]
	s_nop 0
	v_cmp_gt_f32_e64 s[6:7], s39, v184
	v_mul_f32_e32 v64, 0x4b800000, v184
	v_cmp_gt_f32_e32 vcc, s39, v185
	v_cndmask_b32_e64 v64, v184, v64, s[6:7]
	v_rsq_f32_e32 v64, v64
	s_nop 0
	v_mul_f32_e32 v65, 0x45800000, v64
	v_cndmask_b32_e64 v184, v64, v65, s[6:7]
	s_and_saveexec_b64 s[6:7], s[40:41]
	s_movk_i32 s34, 0x1600
	s_cbranch_execz .LBB0_293
	v_pk_mul_f32 v[66:67], v[110:111], v[186:187] op_sel_hi:[1,0]
	v_pk_mul_f32 v[64:65], v[108:109], v[186:187] op_sel_hi:[1,0]
	ds_write_b128 v204, v[64:67]
	v_pk_mul_f32 v[66:67], v[106:107], v[186:187] op_sel_hi:[1,0]
	v_pk_mul_f32 v[64:65], v[104:105], v[186:187] op_sel_hi:[1,0]
	ds_write_b128 v204, v[64:67] offset:16
	v_pk_mul_f32 v[66:67], v[14:15], v[184:185] op_sel_hi:[1,0]
	v_pk_mul_f32 v[64:65], v[12:13], v[184:185] op_sel_hi:[1,0]
	ds_write_b128 v205, v[64:67]
	v_pk_mul_f32 v[66:67], v[10:11], v[184:185] op_sel_hi:[1,0]
	v_pk_mul_f32 v[64:65], v[8:9], v[184:185] op_sel_hi:[1,0]
	ds_write_b128 v204, v[64:67] offset:2064
